# HGRN state item: k_inv tile via 4 wide loads + LDS slab + ds_read_b64_tr_b16 instead of 32 two-byte gathers
# baseline (speedup 1.0000x reference)
.LBB0_569:
	s_add_u32 s46, s62, 0x1200100
	s_addc_u32 s47, s63, 0
	s_sub_i32 s2, s33, s82
	s_addk_i32 s2, 0x80
	v_bfe_u32 v189, v0, 5, 1
	s_cmpk_gt_u32 s2, 0x7f
	v_lshrrev_b32_e32 v188, 6, v0
	v_and_b32_e32 v156, 31, v0
	v_lshrrev_b32_e32 v124, 4, v0
	v_lshlrev_b32_e32 v122, 4, v189
	v_lshlrev_b32_e32 v123, 13, v189
	s_cbranch_scc1 .LBB0_577
	v_lshl_or_b32 v1, v188, 5, v156
	s_movk_i32 s0, 0x110
	v_lshlrev_b32_e32 v2, 4, v0
	s_mov_b32 s1, 0
	v_mad_u32_u24 v1, v1, s0, 0
	v_and_b32_e32 v2, 0xf0, v2
	s_lshr_b32 s0, s2, 1
	v_add_u32_e32 v4, 0, v2
	s_and_b32 s3, s2, 1
	s_lshl_b64 s[6:7], s[0:1], 15
	v_and_b32_e32 v2, 15, v0
	v_lshlrev_b32_e32 v6, 7, v124
	s_lshl_b64 s[8:9], s[0:1], 20
	s_lshl_b32 s10, s3, 5
	v_lshlrev_b32_e32 v3, 3, v2
	v_lshl_or_b32 v6, s3, 12, v6
	v_lshl_or_b32 v36, v2, 4, s6
	v_lshlrev_b32_e32 v2, 6, v188
	v_or3_b32 v34, s8, v3, v6
	v_or3_b32 v2, v2, s10, v156
	v_lshrrev_b32_e32 v3, 1, v0
	s_lshl_b64 s[4:5], s[0:1], 19
	v_lshlrev_b32_e32 v2, 6, v2
	v_and_b32_e32 v3, 16, v3
	s_lshl_b32 s11, s2, 18
	v_or3_b32 v38, s4, v2, v3
	v_lshlrev_b32_e32 v2, 9, v0
	v_mov_b32_e32 v3, 0x1c38000
	s_lshl_b32 s2, s2, 6
	v_bitop3_b32 v2, s11, v3, v2 bitop3:0xc8
	s_and_b32 s2, s2, 0x380
	v_or_b32_e32 v2, s2, v2
	v_lshlrev_b32_e32 v3, 1, v156
	v_or3_b32 v2, v123, v3, v2
	v_or_b32_e32 v64, 0x5c40, v2
	v_mov_b32_e32 v65, 0
	s_mov_b64 s[2:3], 0x15800400
	v_mov_b32_e32 v39, s5
	v_lshl_add_u64 v[40:41], v[64:65], 0, s[2:3]
	v_or_b32_e32 v64, 64, v2
	s_mov_b64 s[4:5], 0x15800c00
	v_lshl_add_u64 v[42:43], v[64:65], 0, s[4:5]
	v_or_b32_e32 v64, 0x5840, v2
	v_lshl_add_u64 v[44:45], v[64:65], 0, s[2:3]
	v_or_b32_e32 v64, 0x5440, v2
	v_lshl_add_u64 v[46:47], v[64:65], 0, s[2:3]
	v_or_b32_e32 v64, 0x5040, v2
	v_lshl_add_u64 v[48:49], v[64:65], 0, s[2:3]
	v_or_b32_e32 v64, 0x4c40, v2
	v_lshl_add_u64 v[52:53], v[64:65], 0, s[2:3]
	v_or_b32_e32 v64, 0x4840, v2
	v_lshl_add_u64 v[54:55], v[64:65], 0, s[2:3]
	v_or_b32_e32 v64, 0x1000, v2
	v_lshl_add_u64 v[56:57], v[64:65], 0, s[2:3]
	v_or_b32_e32 v64, 0x1400, v2
	v_lshl_add_u64 v[58:59], v[64:65], 0, s[2:3]
	v_or_b32_e32 v64, 0x1800, v2
	v_lshl_add_u64 v[60:61], v[64:65], 0, s[2:3]
	v_or_b32_e32 v64, 0x1c00, v2
	v_lshl_add_u64 v[62:63], v[64:65], 0, s[2:3]
	v_or_b32_e32 v64, 0x4000, v2
	v_lshl_add_u64 v[66:67], v[64:65], 0, s[2:3]
	v_or_b32_e32 v64, 0x4400, v2
	v_lshl_add_u64 v[68:69], v[64:65], 0, s[2:3]
	v_or_b32_e32 v64, 0x4800, v2
	v_lshl_add_u64 v[70:71], v[64:65], 0, s[2:3]
	v_or_b32_e32 v64, 0x4c00, v2
	v_lshl_add_u64 v[72:73], v[64:65], 0, s[2:3]
	v_or_b32_e32 v64, 0x5000, v2
	v_lshl_add_u64 v[74:75], v[64:65], 0, s[2:3]
	v_or_b32_e32 v64, 0x5400, v2
	v_lshl_add_u64 v[76:77], v[64:65], 0, s[2:3]
	v_or_b32_e32 v64, 0x5800, v2
	v_lshl_add_u64 v[78:79], v[64:65], 0, s[2:3]
	v_or_b32_e32 v64, 0x5c00, v2
	v_lshl_add_u64 v[80:81], v[64:65], 0, s[2:3]
	v_or_b32_e32 v64, 0x1040, v2
	v_lshl_add_u64 v[82:83], v[64:65], 0, s[2:3]
	v_or_b32_e32 v64, 0x1440, v2
	v_lshl_add_u64 v[84:85], v[64:65], 0, s[2:3]
	v_or_b32_e32 v64, 0x1840, v2
	v_lshl_add_u64 v[86:87], v[64:65], 0, s[2:3]
	v_or_b32_e32 v64, 0x1c40, v2
	v_lshl_add_u64 v[88:89], v[64:65], 0, s[2:3]
	v_or_b32_e32 v64, 0x4040, v2
	v_mul_u32_u24_e32 v5, 0x110, v124
	v_mov_b32_e32 v3, v65
	v_lshl_add_u64 v[90:91], v[64:65], 0, s[2:3]
	v_or_b32_e32 v64, 0x4440, v2
	v_mov_b32_e32 v35, s9
	v_mov_b32_e32 v37, s7
	s_mov_b32 s10, 16
	v_lshl_add_u64 v[50:51], v[2:3], 0, s[4:5]
	v_lshl_add_u64 v[92:93], v[64:65], 0, s[2:3]
	s_mov_b32 s11, 0x17800000
	s_mov_b32 s12, 0x1200000
	s_mov_b32 s13, 0x5040100
	v_add_u32_e32 v1, v1, v122
	v_add_u32_e32 v125, v4, v5
	s_mov_b32 s14, 0xd800000
	s_mov_b32 s15, 0xd802000
	s_mov_b32 s16, 0xd804000
	s_mov_b32 s17, 0xd806000
	s_mov_b32 s18, 0xd808000
	s_mov_b32 s19, 0xd80a000
	s_mov_b32 s20, 0xd80c000
	s_mov_b32 s21, 0xd80e000
	s_mov_b64 s[2:3], 0x10000
	s_mov_b64 s[4:5], 0x800
	s_mov_b64 s[6:7], 0x8000
	s_mov_b64 s[8:9], 0x40000
	v_mov_b32_e32 v64, v65
	v_mov_b32_e32 v94, v65
	v_mov_b32_e32 v95, v65
	v_and_b32_e32 v190, 0x1c38380, v2
	v_bfe_u32 v191, v0, 3, 3
	v_lshl_or_b32 v190, v191, 12, v190
	v_and_b32_e32 v210, 7, v0
	v_lshl_or_b32 v190, v210, 4, v190
	v_lshlrev_b32_e32 v210, 4, v210
	v_mul_u32_u24_e32 v211, 0x300, v191
	v_add_u32_e32 v210, v210, v211
	v_mul_u32_u24_e32 v211, 0x1800, v188
	v_add_u32_e32 v211, 0x12000, v211
	v_add_u32_e32 v210, v210, v211
	v_mul_u32_u24_e32 v191, 0x600, v189
	v_add_u32_e32 v211, v211, v191
	v_bfe_u32 v191, v0, 2, 2
	v_mul_u32_u24_e32 v191, 0xc0, v191
	v_add_u32_e32 v211, v211, v191
	v_bfe_u32 v191, v0, 4, 1
	v_lshl_add_u32 v211, v191, 5, v211
	v_and_b32_e32 v191, 3, v0
	v_lshl_add_u32 v211, v191, 3, v211
	v_mov_b32_e32 v191, 0
	s_mov_b64 s[22:23], 0x15800400
	v_lshl_add_u64 v[190:191], v[190:191], 0, s[22:23]
.LBB0_571:
	v_lshl_add_u64 v[32:33], s[62:63], 0, v[38:39]
	v_lshl_add_u64 v[192:193], s[62:63], 0, v[190:191]
	global_load_dwordx4 v[194:197], v[192:193], off
	global_load_dwordx4 v[198:201], v[192:193], off offset:1024
	global_load_dwordx4 v[202:205], v[192:193], off offset:2048
	global_load_dwordx4 v[206:209], v[192:193], off offset:3072
	v_lshl_add_u64 v[190:191], v[190:191], 0, s[8:9]
	v_add_co_u32_e32 v2, vcc, s11, v32
	v_lshl_add_u64 v[102:103], s[62:63], 0, v[36:37]
	s_nop 0
	s_nop 1
	v_addc_co_u32_e32 v3, vcc, 0, v33, vcc
	v_add_co_u32_e32 v4, vcc, s12, v102
	v_lshl_add_u64 v[126:127], s[62:63], 0, v[34:35]
	s_nop 0
	s_nop 1
	v_addc_co_u32_e32 v5, vcc, 0, v103, vcc
	v_add_co_u32_e32 v144, vcc, s14, v126
	v_cvt_pk_bf16_f32 v120, v64, v65
	s_nop 0
	s_nop 1
	v_addc_co_u32_e32 v145, vcc, 0, v127, vcc
	v_add_co_u32_e32 v146, vcc, s15, v126
	v_cvt_pk_bf16_f32 v121, v94, v95
	s_nop 0
	s_nop 1
	v_addc_co_u32_e32 v147, vcc, 0, v127, vcc
	v_add_co_u32_e32 v148, vcc, s16, v126
	s_add_i32 s10, s10, -1
	s_nop 0
	s_nop 1
	v_addc_co_u32_e32 v149, vcc, 0, v127, vcc
	v_add_co_u32_e32 v150, vcc, s17, v126
	v_lshl_add_u64 v[34:35], v[34:35], 0, s[2:3]
	s_nop 0
	s_nop 1
	v_addc_co_u32_e32 v151, vcc, 0, v127, vcc
	v_add_co_u32_e32 v152, vcc, s18, v126
	s_nop 1
	v_addc_co_u32_e32 v153, vcc, 0, v127, vcc
	v_add_co_u32_e32 v154, vcc, s19, v126
	s_nop 0
	s_nop 1
	v_addc_co_u32_e32 v155, vcc, 0, v127, vcc
	v_add_co_u32_e32 v158, vcc, s20, v126
	v_lshl_add_u64 v[36:37], v[36:37], 0, s[4:5]
	s_nop 0
	s_nop 1
	v_addc_co_u32_e32 v159, vcc, 0, v127, vcc
	v_add_co_u32_e32 v160, vcc, s21, v126
	v_lshl_add_u64 v[38:39], v[38:39], 0, s[6:7]
	s_nop 0
	s_nop 1
	v_addc_co_u32_e32 v161, vcc, 0, v127, vcc
	global_load_dwordx4 v[18:21], v[2:3], off offset:1024
	global_load_dwordx4 v[96:99], v[2:3], off offset:1056
	global_load_dwordx4 v[100:103], v[4:5], off offset:1024
	global_load_dwordx4 v[104:107], v[4:5], off offset:1280
	global_load_dwordx4 v[108:111], v[4:5], off offset:1536
	global_load_dwordx4 v[112:115], v[4:5], off offset:1792
	global_load_dwordx4 v[116:119], v[4:5], off offset:2048
	global_load_dwordx4 v[126:129], v[4:5], off offset:2304
	global_load_dwordx4 v[130:133], v[4:5], off offset:2560
	global_load_dwordx4 v[134:137], v[4:5], off offset:2816
	s_waitcnt vmcnt(10)
	ds_write_b128 v210, v[194:197]
	ds_write_b128 v210, v[198:201] offset:192
	ds_write_b128 v210, v[202:205] offset:384
	ds_write_b128 v210, v[206:209] offset:576
	ds_read_b64_tr_b16 v[2:3], v211
	ds_read_b64_tr_b16 v[4:5], v211 offset:768
	ds_read_b64_tr_b16 v[22:23], v211 offset:64
	ds_read_b64_tr_b16 v[24:25], v211 offset:832
	ds_read_b64_tr_b16 v[212:213], v211 offset:3072
	ds_read_b64_tr_b16 v[214:215], v211 offset:3840
	ds_read_b64_tr_b16 v[216:217], v211 offset:3136
	ds_read_b64_tr_b16 v[218:219], v211 offset:3904
	s_waitcnt lgkmcnt(0)
	s_barrier
	s_waitcnt vmcnt(9)
	v_mfma_f32_32x32x16_bf16 v[2:17], v[2:5], v[18:21], 0
	v_mfma_f32_32x32x16_bf16 v[18:33], v[22:25], v[18:21], 0
	s_waitcnt vmcnt(8)
	v_mfma_f32_32x32x16_bf16 v[2:17], v[212:215], v[96:99], v[2:17]
	v_mfma_f32_32x32x16_bf16 v[18:33], v[216:219], v[96:99], v[18:33]
	s_nop 10
	ds_write_b128 v1, v[2:5]
	ds_write_b128 v1, v[6:9] offset:32
	ds_write_b128 v1, v[10:13] offset:64
	ds_write_b128 v1, v[14:17] offset:96
	s_nop 3
	ds_write_b128 v1, v[18:21] offset:128
	ds_write_b128 v1, v[22:25] offset:160
	ds_write_b128 v1, v[26:29] offset:192
	ds_write_b128 v1, v[30:33] offset:224
	s_waitcnt lgkmcnt(0)
	s_barrier
	global_store_dwordx2 v[144:145], v[120:121], off offset:1024
	ds_read_b128 v[2:5], v125
	ds_read_b128 v[6:9], v125 offset:8704
	ds_read_b128 v[10:13], v125 offset:17408
	ds_read_b128 v[14:17], v125 offset:26112
	ds_read_b128 v[18:21], v125 offset:34816
	ds_read_b128 v[22:25], v125 offset:43520
	ds_read_b128 v[26:29], v125 offset:52224
	ds_read_b128 v[30:33], v125 offset:60928
	s_waitcnt lgkmcnt(7)
	v_pk_add_f32 v[2:3], v[64:65], v[2:3]
	v_pk_add_f32 v[4:5], v[94:95], v[4:5]
	s_waitcnt vmcnt(8)
	v_pk_mul_f32 v[94:95], v[100:101], v[2:3]
	v_pk_mul_f32 v[64:65], v[102:103], v[4:5]
	s_waitcnt lgkmcnt(6)
	v_pk_fma_f32 v[2:3], v[100:101], v[2:3], v[6:7]
	v_pk_fma_f32 v[4:5], v[102:103], v[4:5], v[8:9]
	v_cvt_pk_bf16_f32 v6, v94, v95
	v_cvt_pk_bf16_f32 v7, v64, v65
	s_waitcnt vmcnt(7)
	v_pk_mul_f32 v[8:9], v[106:107], v[4:5]
	v_pk_mul_f32 v[64:65], v[104:105], v[2:3]
	s_waitcnt lgkmcnt(5)
	v_pk_fma_f32 v[4:5], v[106:107], v[4:5], v[12:13]
	v_pk_fma_f32 v[2:3], v[104:105], v[2:3], v[10:11]
	global_store_dwordx2 v[146:147], v[6:7], off offset:1024
	v_cvt_pk_bf16_f32 v6, v64, v65
	v_cvt_pk_bf16_f32 v7, v8, v9
	s_waitcnt vmcnt(7)
	v_pk_mul_f32 v[8:9], v[110:111], v[4:5]
	v_pk_mul_f32 v[10:11], v[108:109], v[2:3]
	s_waitcnt lgkmcnt(4)
	v_pk_fma_f32 v[4:5], v[110:111], v[4:5], v[16:17]
	v_pk_fma_f32 v[2:3], v[108:109], v[2:3], v[14:15]
	global_store_dwordx2 v[148:149], v[6:7], off offset:1024
	v_cvt_pk_bf16_f32 v6, v10, v11
	v_cvt_pk_bf16_f32 v7, v8, v9
	s_waitcnt vmcnt(7)
	v_pk_mul_f32 v[8:9], v[114:115], v[4:5]
	v_pk_mul_f32 v[10:11], v[112:113], v[2:3]
	s_waitcnt lgkmcnt(3)
	v_pk_fma_f32 v[4:5], v[114:115], v[4:5], v[20:21]
	v_pk_fma_f32 v[2:3], v[112:113], v[2:3], v[18:19]
	global_store_dwordx2 v[150:151], v[6:7], off offset:1024
	v_cvt_pk_bf16_f32 v6, v10, v11
	v_cvt_pk_bf16_f32 v7, v8, v9
	s_waitcnt vmcnt(7)
	v_pk_mul_f32 v[8:9], v[118:119], v[4:5]
	v_pk_mul_f32 v[10:11], v[116:117], v[2:3]
	s_waitcnt lgkmcnt(2)
	v_pk_fma_f32 v[4:5], v[118:119], v[4:5], v[24:25]
	v_pk_fma_f32 v[2:3], v[116:117], v[2:3], v[22:23]
	global_store_dwordx2 v[152:153], v[6:7], off offset:1024
	v_cvt_pk_bf16_f32 v6, v10, v11
	v_cvt_pk_bf16_f32 v7, v8, v9
	s_waitcnt vmcnt(7)
	v_pk_mul_f32 v[8:9], v[128:129], v[4:5]
	v_pk_mul_f32 v[10:11], v[126:127], v[2:3]
	s_waitcnt lgkmcnt(1)
	v_pk_fma_f32 v[4:5], v[128:129], v[4:5], v[28:29]
	v_pk_fma_f32 v[2:3], v[126:127], v[2:3], v[26:27]
	global_store_dwordx2 v[154:155], v[6:7], off offset:1024
	v_cvt_pk_bf16_f32 v6, v10, v11
	v_cvt_pk_bf16_f32 v7, v8, v9
	s_waitcnt vmcnt(7)
	v_pk_mul_f32 v[8:9], v[132:133], v[4:5]
	v_pk_mul_f32 v[10:11], v[130:131], v[2:3]
	s_waitcnt lgkmcnt(0)
	v_pk_fma_f32 v[4:5], v[132:133], v[4:5], v[32:33]
	v_pk_fma_f32 v[2:3], v[130:131], v[2:3], v[30:31]
	s_cmp_eq_u32 s10, 0
	global_store_dwordx2 v[158:159], v[6:7], off offset:1024
	v_cvt_pk_bf16_f32 v6, v10, v11
	v_cvt_pk_bf16_f32 v7, v8, v9
	s_waitcnt vmcnt(7)
	v_pk_mul_f32 v[94:95], v[136:137], v[4:5]
	v_pk_mul_f32 v[64:65], v[134:135], v[2:3]
	global_store_dwordx2 v[160:161], v[6:7], off offset:1024
	s_cbranch_scc0 .LBB0_571
	s_waitcnt vmcnt(0)
	s_barrier
	s_and_saveexec_b64 s[2:3], s[44:45]
	s_cbranch_execz .LBB0_576
	s_mov_b64 s[4:5], exec
	buffer_wbl2 sc1
	s_waitcnt vmcnt(0)
	s_waitcnt vmcnt(0)
	v_mbcnt_lo_u32_b32 v1, s4, 0
	v_mbcnt_hi_u32_b32 v1, s5, v1
	v_cmp_eq_u32_e32 vcc, 0, v1
	s_and_saveexec_b64 s[6:7], vcc
	s_cbranch_execz .LBB0_575
	s_lshl_b64 s[0:1], s[0:1], 2
	s_add_u32 s0, s46, s0
	s_addc_u32 s1, s47, s1
	s_bcnt1_i32_b64 s4, s[4:5]
	v_mov_b32_e32 v1, 0
	v_mov_b32_e32 v2, s4
	global_atomic_add v1, v2, s[0:1]
	global_atomic_add v1, v2, s[46:47] offset:256
